# seam2at: the two arrival atomics of the split MIX1->MIX2 seam overlapped (one wait for both); on top of xbpre
# baseline (speedup 1.0000x reference)
.LBB0_1105:
	v_readlane_b32 s2, v254, 23
	v_readlane_b32 s3, v254, 24
	s_andn2_b64 vcc, exec, s[2:3]
	s_cbranch_vccnz .LBB0_1153
	s_mov_b64 s[4:5], exec
	v_mbcnt_lo_u32_b32 v3, s4, 0
	v_mbcnt_hi_u32_b32 v3, s5, v3
	v_cmp_eq_u32_e32 vcc, 0, v3
	s_and_saveexec_b64 s[2:3], vcc
	s_cbranch_execz .LBB0_1108
	v_readlane_b32 s6, v254, 4
	s_lshl_b32 s6, s6, 2
	s_bcnt1_i32_b64 s4, s[4:5]
	v_mov_b32_e32 v4, s6
	v_mov_b32_e32 v5, s4
	global_atomic_add v7, v4, v5, s[12:13] sc0
.LBB0_1108:
	s_or_b64 exec, exec, s[2:3]
	v_readlane_b32 s4, v254, 25
	v_readlane_b32 s5, v254, 26
	s_cmp_lg_u64 s[4:5], 0
	s_cselect_b64 s[2:3], -1, 0
	s_cmp_eq_u64 s[4:5], 0
	s_cbranch_scc1 .LBB0_1146
	s_mov_b64 s[6:7], exec
	v_mbcnt_lo_u32_b32 v4, s6, 0
	v_mbcnt_hi_u32_b32 v4, s7, v4
	v_cmp_eq_u32_e32 vcc, 0, v4
	s_and_saveexec_b64 s[4:5], vcc
	s_cbranch_execz .LBB0_1111
	v_readlane_b32 s9, v254, 4
	s_bcnt1_i32_b64 s6, s[6:7]
	s_lshl_b32 s9, s9, 2
	v_mov_b32_e32 v6, s6
	v_readlane_b32 s6, v254, 25
	v_mov_b32_e32 v5, s9
	v_readlane_b32 s7, v254, 26
	s_nop 4
	global_atomic_add v5, v5, v6, s[6:7] sc0
.LBB0_1111:
	s_or_b64 exec, exec, s[4:5]
	s_waitcnt vmcnt(0)
	v_readfirstlane_b32 s8, v7
	v_readfirstlane_b32 s4, v5
	s_nop 1
	v_add3_u32 v4, s4, v4, 1
	v_add3_u32 v3, s8, v3, 1
	v_cmp_eq_u32_e32 vcc, v3, v2
	s_and_saveexec_b64 s[4:5], vcc
	s_cbranch_execnz .LBB0_1147
	s_branch .LBB0_1149

.LBB0_1146:
	s_waitcnt vmcnt(0)
	v_readfirstlane_b32 s8, v7
	v_mov_b32_e32 v4, 1
	v_add3_u32 v3, s8, v3, 1
	v_cmp_eq_u32_e32 vcc, v3, v2
	s_and_saveexec_b64 s[4:5], vcc
	s_cbranch_execz .LBB0_1149
